# single-round GEMM phases: every workgroup runs its GEMM tile first and its split-K tail item last (instead of alternating by workgroup parity)
# baseline (speedup 1.0000x reference)
; __device__ __forceinline__ int opaque_tid() { int t = threadIdx.x; asm volatile("" : "+v"(t)); return t; }
; #define PG8_BAR __builtin_amdgcn_s_barrier()
; template <class Epi>
; __device__ __forceinline__ void gemm_phase(LAS unsigned char* lds, const Gemm g, const StaticOrder& S, const Epi& E) {
;     const int tid = opaque_tid(), wid = __builtin_amdgcn_readfirstlane(tid >> 6), lane = tid & 63, wr = wid >> 2, wc = wid & 3, fr = lane & 15, fq = lane >> 4;
;     const int K = g.K, nt = K / BK;
;     unsigned voffA[2], voffB[2];
; #pragma unroll
;     for (int i = 0; i < 2; ++i) { int R, C; stage_rc(tid * 16 + i * 8192, R, C); const int Rb = Epi::PERM ? ((R & ~31) + perm32(R & 31)) : R;
;         voffA[i] = (unsigned)(R * K + C) * 2u; voffB[i] = (unsigned)(Rb * K + C) * 2u; }
;     const size_t kstep = (size_t)(BK * 2);
;     const size_t hstep = (size_t)HALF * K * 2;
;     const size_t tstep = 2 * hstep;
;     const unsigned ldsw = (unsigned)wid * 1024u;
;     const int aoff = lds_byte(wr * 64 + fr, fq * 8), boff = lds_byte(wc * 32 + fr, fq * 8);
;     ...
;     Unit cur, nxt; int ui = 0;
;     if (!S.next(0, cur)) return;
;     f32x4 acc[2][2][4][2];
; #pragma unroll
;     for (int a = 0; a < 2; ++a)
; #pragma unroll
;         for (int b = 0; b < 2; ++b)
; #pragma unroll
;             for (int m = 0; m < 4; ++m)
; #pragma unroll
;                 for (int n = 0; n < 2; ++n) acc[a][b][m][n] = (f32x4){0.f, 0.f, 0.f, 0.f};
;     bf16x8 At[4][2], B0[2][2], B1[2][2];
;     const char* cA = (const char*)g.A + (size_t)cur.pm * tstep; const char* cB = (const char*)g.Bt + (size_t)cur.pn * tstep;
;     PG8_STAGE(PG8_SB(0, 0), cB, voffB); PG8_STAGE(PG8_SB(0, 1), cB + hstep, voffB); PG8_STAGE(PG8_SA(0, 0), cA, voffA); PG8_STAGE(PG8_SA(0, 1), cA + hstep, voffA);
;     if (wr == 1) PG8_BAR;
; __global__ void __launch_bounds__(512, 2) mega(Params KP) {
;     ...
;               pg8::Gemm g{(const bf16_t*)(ws + WS_HG), (const bf16_t*)(ws + WS_WA) + (size_t)l * D * D, MM, D, D}; EpiYa E{(bf16_t*)(ws + WS_T), (const bf16_t*)(ws + WS_Z)}; { int np = 2; asm volatile("" : "+s"(np)); for (int pass = 0; pass < np; ++pass) { if ((pass == 0) == ((bid & 1) != 0)) tail_splitk<2, 4>(lds, g.A, g.Bt, D, MM, 8, 0, 16, 0, E); else pg8::gemm_phase<EpiYa>(lds, g, S, E); } } }
.LBB0_692:
	s_cmp_lg_u32 s74, 0
	s_cselect_b64 s[0:1], -1, 0
	v_cndmask_b32_e64 v0, 0, 1, s[0:1]
	v_mov_b32_e32 v2, 0
	v_cmp_eq_u32_e32 vcc, v0, v2
	s_mov_b64 s[0:1], -1
	s_cbranch_vccz .LBB0_714
	v_mov_b32_e32 v8, v188
	s_andn2_b64 vcc, exec, s[42:43]
	v_readfirstlane_b32 s4, v8
	s_cbranch_vccnz .LBB0_713
	v_lshlrev_b32_e32 v0, 4, v8
	v_add_u32_e32 v3, 0x2000, v0
	v_ashrrev_i32_e32 v2, 31, v3
	v_lshrrev_b32_e32 v2, 22, v2
	v_add_u32_e32 v2, v3, v2
	v_ashrrev_i32_e32 v2, 10, v2
	v_lshlrev_b32_e32 v4, 5, v2
	v_and_b32_e32 v5, 32, v4
	v_mul_i32_i24_e32 v4, 0x400, v2
	v_sub_u32_e32 v3, v3, v4
	v_lshrrev_b32_e32 v4, 4, v3
	v_bitop3_b32 v4, v4, v3, 32 bitop3:0x6c
	v_ashrrev_i32_e32 v3, 31, v4
	v_lshrrev_b32_e32 v3, 26, v3
	v_add_u32_e32 v6, v4, v3
	v_ashrrev_i32_e32 v3, 6, v6
	v_and_b32_e32 v6, 0xc0, v6
	v_sub_u32_e32 v4, v4, v6
	v_ashrrev_i16_sdwa v4, v191, sext(v4) dst_sel:DWORD dst_unused:UNUSED_PAD src0_sel:DWORD src1_sel:BYTE_0
	v_lshlrev_b32_e32 v6, 3, v2
	v_bfe_i32 v4, v4, 0, 16
	v_and_b32_e32 v6, 0x1ffff0, v6
	v_add_u32_e32 v5, v5, v4
	v_add_lshl_u32 v6, v3, v6, 11
	s_waitcnt vmcnt(0)
	v_lshl_add_u32 v142, v5, 1, v6
	v_ashrrev_i32_e32 v5, 31, v8
	v_lshrrev_b32_e32 v5, 26, v5
	v_add_u32_e32 v5, v8, v5
	v_ashrrev_i32_e32 v5, 6, v5
	v_lshlrev_b32_e32 v6, 5, v5
	v_and_b32_e32 v9, 32, v6
	v_bfe_i32 v6, v8, 27, 1
	v_lshrrev_b32_e32 v6, 22, v6
	v_add_u32_e32 v6, v0, v6
	v_and_b32_e32 v6, 0xfffffc00, v6
	v_sub_u32_e32 v0, v0, v6
	v_lshrrev_b32_e32 v6, 4, v0
	v_bitop3_b32 v7, v6, v0, 32 bitop3:0x6c
	v_ashrrev_i32_e32 v0, 31, v0
	v_lshrrev_b32_e32 v0, 26, v0
	v_add_u32_e32 v0, v7, v0
	v_ashrrev_i32_e32 v6, 6, v0
	v_mul_i32_i24_e32 v0, 64, v6
	v_sub_u32_e32 v0, v7, v0
	v_ashrrev_i16_sdwa v0, v191, sext(v0) dst_sel:DWORD dst_unused:UNUSED_PAD src0_sel:DWORD src1_sel:BYTE_0
	v_bfe_i32 v7, v0, 0, 16
	s_ashr_i32 s5, s4, 6
	v_add_u32_e32 v0, v9, v7
	v_lshlrev_b32_e32 v9, 3, v5
	s_lshl_b32 s45, s5, 10
	v_and_b32_e32 v9, 0x1ffff0, v9
	v_add_lshl_u32 v9, v6, v9, 11
	s_add_i32 s76, s45, 0
	v_lshl_add_u32 v0, v0, 1, v9
	s_add_i32 m0, s76, 0x10000
	s_add_i32 s77, s76, 0x2000
	global_load_lds_dwordx4 v0, s[46:47]
	s_add_i32 m0, s76, 0x12000
	s_add_i32 s78, s76, 0x4000
	global_load_lds_dwordx4 v142, s[46:47]
	s_add_i32 m0, s76, 0x14000
	s_add_i32 s79, s76, 0x6000
	global_load_lds_dwordx4 v0, s[48:49]
	s_add_i32 m0, s76, 0x16000
	s_ashr_i32 s12, s4, 8
	global_load_lds_dwordx4 v142, s[48:49]
	s_mov_b32 m0, s76
	s_cmp_eq_u32 s12, 1
	global_load_lds_dwordx4 v0, s[50:51]
	s_mov_b32 m0, s77
	s_cselect_b64 s[0:1], -1, 0
	global_load_lds_dwordx4 v142, s[50:51]
	s_mov_b32 m0, s78
	s_cmp_lg_u32 s12, 1
	global_load_lds_dwordx4 v0, s[52:53]
	s_mov_b32 m0, s79
	s_nop 0
	global_load_lds_dwordx4 v142, s[52:53]
	s_cbranch_scc1 .LBB0_696
	s_barrier

; __device__ __forceinline__ int opaque_tid() { int t = threadIdx.x; asm volatile("" : "+v"(t)); return t; }
; #define PG8_BAR __builtin_amdgcn_s_barrier()
; template <class Epi>
; __device__ __forceinline__ void gemm_phase(LAS unsigned char* lds, const Gemm g, const StaticOrder& S, const Epi& E) {
;     const int tid = opaque_tid(), wid = __builtin_amdgcn_readfirstlane(tid >> 6), lane = tid & 63, wr = wid >> 2, wc = wid & 3, fr = lane & 15, fq = lane >> 4;
;     const int K = g.K, nt = K / BK;
;     unsigned voffA[2], voffB[2];
; #pragma unroll
;     for (int i = 0; i < 2; ++i) { int R, C; stage_rc(tid * 16 + i * 8192, R, C); const int Rb = Epi::PERM ? ((R & ~31) + perm32(R & 31)) : R;
;         voffA[i] = (unsigned)(R * K + C) * 2u; voffB[i] = (unsigned)(Rb * K + C) * 2u; }
;     const size_t kstep = (size_t)(BK * 2);
;     const size_t hstep = (size_t)HALF * K * 2;
;     const size_t tstep = 2 * hstep;
;     const unsigned ldsw = (unsigned)wid * 1024u;
;     const int aoff = lds_byte(wr * 64 + fr, fq * 8), boff = lds_byte(wc * 32 + fr, fq * 8);
;     ...
;     Unit cur, nxt; int ui = 0;
;     if (!S.next(0, cur)) return;
;     f32x4 acc[2][2][4][2];
; #pragma unroll
;     for (int a = 0; a < 2; ++a)
; #pragma unroll
;         for (int b = 0; b < 2; ++b)
; #pragma unroll
;             for (int m = 0; m < 4; ++m)
; #pragma unroll
;                 for (int n = 0; n < 2; ++n) acc[a][b][m][n] = (f32x4){0.f, 0.f, 0.f, 0.f};
;     bf16x8 At[4][2], B0[2][2], B1[2][2];
;     const char* cA = (const char*)g.A + (size_t)cur.pm * tstep; const char* cB = (const char*)g.Bt + (size_t)cur.pn * tstep;
;     PG8_STAGE(PG8_SB(0, 0), cB, voffB); PG8_STAGE(PG8_SB(0, 1), cB + hstep, voffB); PG8_STAGE(PG8_SA(0, 0), cA, voffA); PG8_STAGE(PG8_SA(0, 1), cA + hstep, voffA);
;     if (wr == 1) PG8_BAR;
; __global__ void __launch_bounds__(512, 2) mega(Params KP) {
;     ...
;               pg8::Gemm g{(const bf16_t*)(ws + WS_OG), (const bf16_t*)(ws + WS_WB) + (size_t)l * D * D, MM, D, D}; EpiMerge E{(const bf16_t*)(ws + WS_T), (const bf16_t*)(ws + WS_Z), (bf16_t*)(ws + WS_MG)}; { int np = 2; asm volatile("" : "+s"(np)); for (int pass = 0; pass < np; ++pass) { if ((pass == 0) == ((bid & 1) != 0)) tail_splitk<2, 4>(lds, g.A, g.Bt, D, MM, 8, 0, 16, 0, E); else pg8::gemm_phase<EpiMerge>(lds, g, S, E); } } } }
.LBB0_776:
	s_cmp_lg_u32 s75, 0
	s_cselect_b64 s[0:1], -1, 0
	v_cndmask_b32_e64 v0, 0, 1, s[0:1]
	v_mov_b32_e32 v2, 0
	v_cmp_eq_u32_e32 vcc, v0, v2
	s_mov_b64 s[0:1], -1
	s_cbranch_vccz .LBB0_798
	v_mov_b32_e32 v8, v188
	s_andn2_b64 vcc, exec, s[52:53]
	v_readfirstlane_b32 s4, v8
	s_cbranch_vccnz .LBB0_797
	v_lshlrev_b32_e32 v0, 4, v8
	v_add_u32_e32 v3, 0x2000, v0
	v_ashrrev_i32_e32 v2, 31, v3
	v_lshrrev_b32_e32 v2, 22, v2
	v_add_u32_e32 v2, v3, v2
	v_ashrrev_i32_e32 v2, 10, v2
	v_lshlrev_b32_e32 v4, 5, v2
	v_and_b32_e32 v5, 32, v4
	v_mul_i32_i24_e32 v4, 0x400, v2
	v_sub_u32_e32 v3, v3, v4
	v_lshrrev_b32_e32 v4, 4, v3
	v_bitop3_b32 v4, v4, v3, 32 bitop3:0x6c
	v_ashrrev_i32_e32 v3, 31, v4
	v_lshrrev_b32_e32 v3, 26, v3
	v_add_u32_e32 v6, v4, v3
	v_ashrrev_i32_e32 v3, 6, v6
	v_and_b32_e32 v6, 0xc0, v6
	v_sub_u32_e32 v4, v4, v6
	v_ashrrev_i16_sdwa v4, v191, sext(v4) dst_sel:DWORD dst_unused:UNUSED_PAD src0_sel:DWORD src1_sel:BYTE_0
	v_lshlrev_b32_e32 v6, 3, v2
	v_bfe_i32 v4, v4, 0, 16
	v_and_b32_e32 v6, 0x1ffff0, v6
	v_add_u32_e32 v5, v5, v4
	v_add_lshl_u32 v6, v3, v6, 11
	s_waitcnt vmcnt(0)
	v_lshl_add_u32 v142, v5, 1, v6
	v_ashrrev_i32_e32 v5, 31, v8
	v_lshrrev_b32_e32 v5, 26, v5
	v_add_u32_e32 v5, v8, v5
	v_ashrrev_i32_e32 v5, 6, v5
	v_lshlrev_b32_e32 v6, 5, v5
	v_and_b32_e32 v9, 32, v6
	v_bfe_i32 v6, v8, 27, 1
	v_lshrrev_b32_e32 v6, 22, v6
	v_add_u32_e32 v6, v0, v6
	v_and_b32_e32 v6, 0xfffffc00, v6
	v_sub_u32_e32 v0, v0, v6
	v_lshrrev_b32_e32 v6, 4, v0
	v_bitop3_b32 v7, v6, v0, 32 bitop3:0x6c
	v_ashrrev_i32_e32 v0, 31, v0
	v_lshrrev_b32_e32 v0, 26, v0
	v_add_u32_e32 v0, v7, v0
	v_ashrrev_i32_e32 v6, 6, v0
	v_mul_i32_i24_e32 v0, 64, v6
	v_sub_u32_e32 v0, v7, v0
	v_ashrrev_i16_sdwa v0, v191, sext(v0) dst_sel:DWORD dst_unused:UNUSED_PAD src0_sel:DWORD src1_sel:BYTE_0
	v_bfe_i32 v7, v0, 0, 16
	s_ashr_i32 s5, s4, 6
	v_add_u32_e32 v0, v9, v7
	v_lshlrev_b32_e32 v9, 3, v5
	s_lshl_b32 s55, s5, 10
	v_and_b32_e32 v9, 0x1ffff0, v9
	v_add_lshl_u32 v9, v6, v9, 11
	s_add_i32 s77, s55, 0
	v_lshl_add_u32 v0, v0, 1, v9
	s_add_i32 m0, s77, 0x10000
	s_add_i32 s78, s77, 0x2000
	global_load_lds_dwordx4 v0, s[56:57]
	s_add_i32 m0, s77, 0x12000
	s_add_i32 s79, s77, 0x4000
	global_load_lds_dwordx4 v142, s[56:57]
	s_add_i32 m0, s77, 0x14000
	s_add_i32 s80, s77, 0x6000
	global_load_lds_dwordx4 v0, s[34:35]
	s_add_i32 m0, s77, 0x16000
	s_ashr_i32 s12, s4, 8
	global_load_lds_dwordx4 v142, s[34:35]
	s_mov_b32 m0, s77
	s_cmp_eq_u32 s12, 1
	global_load_lds_dwordx4 v0, s[10:11]
	s_mov_b32 m0, s78
	s_cselect_b64 s[0:1], -1, 0
	global_load_lds_dwordx4 v142, s[10:11]
	s_mov_b32 m0, s79
	s_cmp_lg_u32 s12, 1
	global_load_lds_dwordx4 v0, s[44:45]
	s_mov_b32 m0, s80
	s_nop 0
	global_load_lds_dwordx4 v142, s[44:45]
	s_cbranch_scc1 .LBB0_780
	s_barrier

; __device__ __forceinline__ int opaque_tid() { int t = threadIdx.x; asm volatile("" : "+v"(t)); return t; }
; #define PG8_BAR __builtin_amdgcn_s_barrier()
; template <class Epi>
; __device__ __forceinline__ void gemm_phase(LAS unsigned char* lds, const Gemm g, const StaticOrder& S, const Epi& E) {
;     const int tid = opaque_tid(), wid = __builtin_amdgcn_readfirstlane(tid >> 6), lane = tid & 63, wr = wid >> 2, wc = wid & 3, fr = lane & 15, fq = lane >> 4;
;     const int K = g.K, nt = K / BK;
;     unsigned voffA[2], voffB[2];
; #pragma unroll
;     for (int i = 0; i < 2; ++i) { int R, C; stage_rc(tid * 16 + i * 8192, R, C); const int Rb = Epi::PERM ? ((R & ~31) + perm32(R & 31)) : R;
;         voffA[i] = (unsigned)(R * K + C) * 2u; voffB[i] = (unsigned)(Rb * K + C) * 2u; }
;     const size_t kstep = (size_t)(BK * 2);
;     const size_t hstep = (size_t)HALF * K * 2;
;     const size_t tstep = 2 * hstep;
;     const unsigned ldsw = (unsigned)wid * 1024u;
;     const int aoff = lds_byte(wr * 64 + fr, fq * 8), boff = lds_byte(wc * 32 + fr, fq * 8);
;     ...
;     Unit cur, nxt; int ui = 0;
;     if (!S.next(0, cur)) return;
;     f32x4 acc[2][2][4][2];
; #pragma unroll
;     for (int a = 0; a < 2; ++a)
; #pragma unroll
;         for (int b = 0; b < 2; ++b)
; #pragma unroll
;             for (int m = 0; m < 4; ++m)
; #pragma unroll
;                 for (int n = 0; n < 2; ++n) acc[a][b][m][n] = (f32x4){0.f, 0.f, 0.f, 0.f};
;     bf16x8 At[4][2], B0[2][2], B1[2][2];
;     const char* cA = (const char*)g.A + (size_t)cur.pm * tstep; const char* cB = (const char*)g.Bt + (size_t)cur.pn * tstep;
;     PG8_STAGE(PG8_SB(0, 0), cB, voffB); PG8_STAGE(PG8_SB(0, 1), cB + hstep, voffB); PG8_STAGE(PG8_SA(0, 0), cA, voffA); PG8_STAGE(PG8_SA(0, 1), cA + hstep, voffA);
;     if (wr == 1) PG8_BAR;
; __global__ void __launch_bounds__(512, 2) mega(Params KP) {
;     ...
;             EpiResid E{(bf16_t*)(ws + WS_XB), (float*)(ws + WS_SS) + (size_t)M * 16}; { int np = 2; asm volatile("" : "+s"(np)); for (int pass = 0; pass < np; ++pass) { if ((pass == 0) == ((bid & 1) != 0)) tail_splitk<2, 4>(lds, g.A, g.Bt, D, MM, 8, 0, 16, 0, E); else pg8::gemm_phase<EpiResid>(lds, g, S, E); } } }
.LBB0_864:
	s_cmp_lg_u32 s80, 0
	s_cselect_b64 s[0:1], -1, 0
	v_cndmask_b32_e64 v0, 0, 1, s[0:1]
	s_waitcnt vmcnt(0) lgkmcnt(0)
	v_mov_b32_e32 v2, 0
	v_cmp_eq_u32_e32 vcc, v0, v2
	s_mov_b64 s[0:1], -1
	s_cbranch_vccz .LBB0_902
	v_mov_b32_e32 v10, v188
	s_andn2_b64 vcc, exec, s[34:35]
	v_readfirstlane_b32 s4, v10
	s_cbranch_vccnz .LBB0_901
	v_lshlrev_b32_e32 v0, 4, v10
	v_add_u32_e32 v3, 0x2000, v0
	v_ashrrev_i32_e32 v2, 31, v3
	v_lshrrev_b32_e32 v2, 22, v2
	v_add_u32_e32 v2, v3, v2
	v_ashrrev_i32_e32 v2, 10, v2
	v_mul_i32_i24_e32 v4, 0x400, v2
	v_sub_u32_e32 v3, v3, v4
	v_lshrrev_b32_e32 v4, 4, v3
	v_bitop3_b32 v5, v4, v3, 32 bitop3:0x6c
	v_ashrrev_i32_e32 v3, 31, v5
	v_lshrrev_b32_e32 v3, 26, v3
	v_add_u32_e32 v6, v5, v3
	v_ashrrev_i32_e32 v3, 6, v6
	v_and_b32_e32 v6, 0xc0, v6
	v_sub_u32_e32 v5, v5, v6
	v_bfe_i32 v6, v10, 27, 1
	v_lshrrev_b32_e32 v6, 22, v6
	v_add_u32_e32 v6, v0, v6
	v_and_b32_e32 v6, 0xfffffc00, v6
	v_sub_u32_e32 v0, v0, v6
	v_lshrrev_b32_e32 v6, 4, v0
	v_bitop3_b32 v9, v6, v0, 32 bitop3:0x6c
	v_ashrrev_i32_e32 v0, 31, v0
	v_lshlrev_b32_e32 v4, 3, v2
	v_lshrrev_b32_e32 v0, 26, v0
	v_and_b32_e32 v4, 0x1ffff0, v4
	v_add_u32_e32 v0, v9, v0
	v_add_u32_e32 v7, v3, v4
	v_lshlrev_b32_e32 v4, 5, v2
	v_ashrrev_i32_e32 v6, 6, v0
	v_ashrrev_i32_e32 v0, 31, v10
	v_and_b32_e32 v4, 32, v4
	v_ashrrev_i16_sdwa v5, v191, sext(v5) dst_sel:DWORD dst_unused:UNUSED_PAD src0_sel:DWORD src1_sel:BYTE_0
	v_lshrrev_b32_e32 v0, 26, v0
	v_lshl_or_b32 v7, v7, 10, v4
	v_bfe_i32 v5, v5, 0, 16
	v_add_u32_e32 v0, v10, v0
	s_waitcnt vmcnt(0)
	v_add_lshl_u32 v142, v7, v5, 1
	v_ashrrev_i32_e32 v7, 6, v0
	v_lshlrev_b32_e32 v0, 3, v7
	v_mul_i32_i24_e32 v11, 64, v6
	s_ashr_i32 s5, s4, 6
	v_and_b32_e32 v0, 0x1ffff0, v0
	v_lshlrev_b32_e32 v8, 5, v7
	v_sub_u32_e32 v9, v9, v11
	s_lshl_b32 s43, s5, 10
	v_add_u32_e32 v0, v6, v0
	v_and_b32_e32 v8, 32, v8
	v_ashrrev_i16_sdwa v9, v191, sext(v9) dst_sel:DWORD dst_unused:UNUSED_PAD src0_sel:DWORD src1_sel:BYTE_0
	v_lshl_or_b32 v0, v0, 10, v8
	v_bfe_i32 v9, v9, 0, 16
	s_add_i32 s82, s43, 0
	v_add_lshl_u32 v0, v0, v9, 1
	s_add_i32 m0, s82, 0x10000
	s_add_i32 s83, s82, 0x2000
	global_load_lds_dwordx4 v0, s[44:45]
	s_add_i32 m0, s82, 0x12000
	s_add_i32 s84, s82, 0x4000
	global_load_lds_dwordx4 v142, s[44:45]
	s_add_i32 m0, s82, 0x14000
	s_add_i32 s85, s82, 0x6000
	global_load_lds_dwordx4 v0, s[46:47]
	s_add_i32 m0, s82, 0x16000
	s_ashr_i32 s30, s4, 8
	global_load_lds_dwordx4 v142, s[46:47]
	s_mov_b32 m0, s82
	s_cmp_eq_u32 s30, 1
	global_load_lds_dwordx4 v0, s[48:49]
	s_mov_b32 m0, s83
	s_cselect_b64 s[0:1], -1, 0
	global_load_lds_dwordx4 v142, s[48:49]
	s_mov_b32 m0, s84
	s_cmp_lg_u32 s30, 1
	global_load_lds_dwordx4 v0, s[50:51]
	s_mov_b32 m0, s85
	s_nop 0
	global_load_lds_dwordx4 v142, s[50:51]
	s_cbranch_scc1 .LBB0_868
	s_barrier

; __device__ __forceinline__ int opaque_tid() { int t = threadIdx.x; asm volatile("" : "+v"(t)); return t; }
; #define PG8_STAGE(bufoff, gbase, voff) do { _Pragma("unroll") for (int _i = 0; _i < 2; ++_i) \
;         __builtin_amdgcn_global_load_lds((const unsigned*)((const char*)(gbase) + (voff)[_i]), (LAS unsigned*)(lds + (bufoff) + ldsw + _i * 8192), 16, 0, 0); } while (0)
; template <class Epi>
; __device__ __forceinline__ void gemm_phase(LAS unsigned char* lds, const Gemm g, const StaticOrder& S, const Epi& E) {
;     const int tid = opaque_tid(), wid = __builtin_amdgcn_readfirstlane(tid >> 6), lane = tid & 63, wr = wid >> 2, wc = wid & 3, fr = lane & 15, fq = lane >> 4;
;     const int K = g.K, nt = K / BK;
;     unsigned voffA[2], voffB[2];
; #pragma unroll
;     for (int i = 0; i < 2; ++i) { int R, C; stage_rc(tid * 16 + i * 8192, R, C); const int Rb = Epi::PERM ? ((R & ~31) + perm32(R & 31)) : R;
;         voffA[i] = (unsigned)(R * K + C) * 2u; voffB[i] = (unsigned)(Rb * K + C) * 2u; }
;     const size_t kstep = (size_t)(BK * 2);
;     const size_t hstep = (size_t)HALF * K * 2;
;     const size_t tstep = 2 * hstep;
;     const unsigned ldsw = (unsigned)wid * 1024u;
;     const int aoff = lds_byte(wr * 64 + fr, fq * 8), boff = lds_byte(wc * 32 + fr, fq * 8);
;     ...
;     Unit cur, nxt; int ui = 0;
;     if (!S.next(0, cur)) return;
;     f32x4 acc[2][2][4][2];
; #pragma unroll
;     for (int a = 0; a < 2; ++a)
; #pragma unroll
;         for (int b = 0; b < 2; ++b)
; #pragma unroll
;             for (int m = 0; m < 4; ++m)
; #pragma unroll
;                 for (int n = 0; n < 2; ++n) acc[a][b][m][n] = (f32x4){0.f, 0.f, 0.f, 0.f};
;     bf16x8 At[4][2], B0[2][2], B1[2][2];
;     const char* cA = (const char*)g.A + (size_t)cur.pm * tstep; const char* cB = (const char*)g.Bt + (size_t)cur.pn * tstep;
;     PG8_STAGE(PG8_SB(0, 0), cB, voffB); PG8_STAGE(PG8_SB(0, 1), cB + hstep, voffB); PG8_STAGE(PG8_SA(0, 0), cA, voffA); PG8_STAGE(PG8_SA(0, 1), cA + hstep, voffA);
;     if (wr == 1) PG8_BAR;
; __global__ void __launch_bounds__(512, 2) mega(Params KP) {
;     ...
;             EpiResid E{(bf16_t*)(ws + WS_XB), (float*)(ws + WS_SS)}; { int np = 2; asm volatile("" : "+s"(np)); for (int pass = 0; pass < np; ++pass) { if ((pass == 0) == ((bid & 1) != 0)) tail_splitk<2, 4>(lds, g.A, g.Bt, DFF, MM, 8, 0, 16, 0, E); else pg8::gemm_phase<EpiResid>(lds, g, S, E); } } }
.LBB0_1122:
	s_cmp_lg_u32 s78, 0
	s_cselect_b64 s[0:1], -1, 0
	v_cndmask_b32_e64 v0, 0, 1, s[0:1]
	s_waitcnt vmcnt(0) lgkmcnt(0)
	v_mov_b32_e32 v2, 0
	v_cmp_eq_u32_e32 vcc, v0, v2
	s_mov_b64 s[0:1], -1
	s_cbranch_vccz .LBB0_1164
	v_mov_b32_e32 v10, v188
	s_andn2_b64 vcc, exec, s[28:29]
	v_readfirstlane_b32 s0, v10
	s_cbranch_vccnz .LBB0_1163
	v_lshlrev_b32_e32 v0, 4, v10
	v_add_u32_e32 v3, 0x2000, v0
	v_ashrrev_i32_e32 v2, 31, v3
	v_lshrrev_b32_e32 v2, 22, v2
	v_add_u32_e32 v2, v3, v2
	v_ashrrev_i32_e32 v2, 10, v2
	v_mul_i32_i24_e32 v4, 0x400, v2
	v_sub_u32_e32 v3, v3, v4
	v_lshrrev_b32_e32 v4, 4, v3
	v_bitop3_b32 v5, v4, v3, 32 bitop3:0x6c
	v_ashrrev_i32_e32 v3, 31, v5
	v_lshrrev_b32_e32 v3, 26, v3
	v_add_u32_e32 v6, v5, v3
	v_ashrrev_i32_e32 v3, 6, v6
	v_and_b32_e32 v6, 0xc0, v6
	v_sub_u32_e32 v5, v5, v6
	v_bfe_i32 v6, v10, 27, 1
	v_lshrrev_b32_e32 v6, 22, v6
	v_add_u32_e32 v6, v0, v6
	v_and_b32_e32 v6, 0xfffffc00, v6
	v_sub_u32_e32 v0, v0, v6
	v_lshrrev_b32_e32 v6, 4, v0
	v_lshlrev_b32_e32 v4, 3, v2
	v_bitop3_b32 v9, v6, v0, 32 bitop3:0x6c
	v_ashrrev_i32_e32 v0, 31, v0
	v_and_b32_e32 v4, 0x3ffff0, v4
	v_lshrrev_b32_e32 v0, 26, v0
	v_add_u32_e32 v4, v3, v4
	s_movk_i32 s4, 0xc00
	v_add_u32_e32 v0, v9, v0
	v_mul_lo_u32 v7, v4, s4
	v_lshlrev_b32_e32 v4, 5, v2
	v_ashrrev_i32_e32 v6, 6, v0
	v_ashrrev_i32_e32 v0, 31, v10
	v_and_b32_e32 v4, 32, v4
	v_ashrrev_i16_sdwa v5, v191, sext(v5) dst_sel:DWORD dst_unused:UNUSED_PAD src0_sel:DWORD src1_sel:BYTE_0
	v_lshrrev_b32_e32 v0, 26, v0
	v_or_b32_e32 v7, v7, v4
	v_bfe_i32 v5, v5, 0, 16
	v_add_u32_e32 v0, v10, v0
	v_add_lshl_u32 v142, v7, v5, 1
	v_ashrrev_i32_e32 v7, 6, v0
	v_lshlrev_b32_e32 v0, 3, v7
	v_and_b32_e32 v0, 0x3ffff0, v0
	v_mul_i32_i24_e32 v11, 64, v6
	s_ashr_i32 s1, s0, 6
	v_add_u32_e32 v0, v6, v0
	v_lshlrev_b32_e32 v8, 5, v7
	v_sub_u32_e32 v9, v9, v11
	s_lshl_b32 s81, s1, 10
	v_mul_lo_u32 v0, v0, s4
	v_and_b32_e32 v8, 32, v8
	v_ashrrev_i16_sdwa v9, v191, sext(v9) dst_sel:DWORD dst_unused:UNUSED_PAD src0_sel:DWORD src1_sel:BYTE_0
	v_or_b32_e32 v0, v0, v8
	v_bfe_i32 v9, v9, 0, 16
	s_add_i32 s82, s81, 0
	v_add_lshl_u32 v0, v0, v9, 1
	s_add_i32 m0, s82, 0x10000
	s_add_i32 s83, s82, 0x2000
	global_load_lds_dwordx4 v0, s[34:35]
	s_add_i32 m0, s82, 0x12000
	s_add_i32 s84, s82, 0x4000
	global_load_lds_dwordx4 v142, s[34:35]
	s_add_i32 m0, s82, 0x14000
	s_add_i32 s85, s82, 0x6000
	global_load_lds_dwordx4 v0, s[42:43]
	s_add_i32 m0, s82, 0x16000
	s_ashr_i32 s4, s0, 8
	global_load_lds_dwordx4 v142, s[42:43]
	s_mov_b32 m0, s82
	s_cmp_eq_u32 s4, 1
	global_load_lds_dwordx4 v0, s[44:45]
	s_mov_b32 m0, s83
	s_cselect_b64 s[52:53], -1, 0
	global_load_lds_dwordx4 v142, s[44:45]
	s_mov_b32 m0, s84
	s_cmp_lg_u32 s4, 1
	global_load_lds_dwordx4 v0, s[46:47]
	s_mov_b32 m0, s85
	s_nop 0
	global_load_lds_dwordx4 v142, s[46:47]
	s_cbranch_scc1 .LBB0_1126
	s_barrier
